# Differential attention: current-tile list byte read issued at the loop top so its LDS latency overlaps the prefetch DMA issue
# baseline (speedup 1.0000x reference)
; #define AWAIT(n) asm volatile("s_waitcnt vmcnt(%0)" :: "n"(n) : "memory")
; #define ABAR() asm volatile("s_waitcnt lgkmcnt(0)\n\ts_barrier" ::: "memory")
;     __device__ __forceinline__ bool wave_skip(int t, int wave) const { const int r = R + (wave >> 1), kr = kr_lo + t, a = r0(r); return kr < a || kr > a + 7; }
;     __device__ __forceinline__ bool wave_skip(int t, int wave) const { return (64 * t + 63 < 32 * wave) || (64 * t > 32 * wave + 159); }
; template <int KSTEPS, class Pol>
; __device__ __forceinline__ void attn_pass(LAS unsigned char* lds, const Pol& P, const bf16_t* qb, int ldq, const bf16_t* kb, int ldk, const bf16_t* vb, int ldv,
;                                           float qs, f32x16 (&O)[4], float& m, float& l) {
;     ...
;     for (int t = 0; t < nt; ++t) {
;         const int st2 = (st >= 1) ? st - 1 : 2;
;         if (t + 2 < nt) dma(t + 2, st2);
;         if (!P.wave_skip(t, wave)) { qk_softmax(st, t); pv_acc(st); }
;         if (t + 1 < nt) { if (t + 2 < nt) AWAIT(NDMA); else AWAIT(0); ABAR(); }
.LBB0_497:
	s_add_i32 s98, s48, 0x18800
	v_mov_b32_e32 v202, s98
	ds_read_u8 v202, v202
	s_add_i32 s36, s48, 2
	s_cmp_ge_i32 s36, s44
	s_cselect_b64 s[2:3], -1, 0
	s_cmp_lt_i32 s36, s44
	s_mov_b64 s[36:37], -1
	s_cbranch_scc1 .LBB0_499
	s_lshl_b32 s51, s49, 15
	s_mov_b64 s[36:37], 0

;     __device__ __forceinline__ void fill(f32x16& S0, f32x16& S1, int qi, int half, int ts, int wave) const {
;         const int t = (int)list[ts];
;         const int x0 = q0 + qi - 64 * t - 4 * half;
;         const int qlo = q0 + 32 * wave;
;         const bool left = 64 * t + 63 < qlo, right = 64 * t > qlo + 31;
;         if (left || right) {
;             const float s = left ? sl : -sl, b0 = -s * (float)x0;
;             const f32x2 s2 = {s, s}, b2 = {b0, b0};
; #pragma unroll
;             for (int i = 0; i < 16; i += 2) {
;                 const int jc = 8 * (i >> 2) + (i & 3);
;                 const f32x2 j0 = {(float)jc, (float)(jc + 1)}, j1 = {(float)(32 + jc), (float)(33 + jc)};
;                 const f32x2 r0 = j0 * s2 + b2, r1 = j1 * s2 + b2;
;                 S0[i] = r0.x; S0[i + 1] = r0.y; S1[i] = r1.x; S1[i + 1] = r1.y;
;             }
;         } else {
;             const float base = (float)x0;
; #pragma unroll
;             for (int i = 0; i < 16; ++i) { const int jc = 8 * (i >> 2) + (i & 3); S0[i] = -sl * fabsf(base - (float)jc); S1[i] = -sl * fabsf(base - (float)(32 + jc)); }
;         }
;     }
.LBB0_501:
	s_waitcnt lgkmcnt(0)
	v_readfirstlane_b32 s36, v202
	s_and_b32 s36, s36, 0xff
	s_lshl_b32 s40, s36, 6
	v_or_b32_e32 v0, s40, v157
	s_or_b32 s36, s40, 63
	v_sub_u32_e32 v0, v150, v0
	s_cmp_lt_i32 s36, s46
	s_cselect_b64 s[36:37], -1, 0
	s_cmp_gt_i32 s40, s47
	v_cvt_f32_i32_e32 v0, v0
	s_cselect_b64 s[40:41], -1, 0
	s_or_b64 s[40:41], s[36:37], s[40:41]
	s_andn2_b64 vcc, exec, s[40:41]
	s_mov_b64 s[40:41], -1
	s_cbranch_vccz .LBB0_503
	v_pk_add_f32 v[2:3], v[0:1], s[18:19] op_sel_hi:[0,1]
	v_pk_add_f32 v[4:5], v[0:1], s[12:13] op_sel_hi:[0,1]
	v_pk_add_f32 v[6:7], v[0:1], s[6:7] op_sel_hi:[0,1]
	v_pk_add_f32 v[8:9], v[0:1], s[16:17] op_sel_hi:[0,1]
	v_pk_add_f32 v[10:11], v[0:1], s[24:25] op_sel_hi:[0,1]
	v_pk_add_f32 v[12:13], v[0:1], s[28:29] op_sel_hi:[0,1]
	v_pk_add_f32 v[14:15], v[0:1], s[4:5] op_sel_hi:[0,1]
	s_mov_b32 s40, 0xc2680000
	v_and_b32_e32 v3, 0x7fffffff, v3
	v_and_b32_e32 v2, 0x7fffffff, v2
	v_and_b32_e32 v5, 0x7fffffff, v5
	v_and_b32_e32 v4, 0x7fffffff, v4
	v_and_b32_e32 v7, 0x7fffffff, v7
	v_and_b32_e32 v6, 0x7fffffff, v6
	v_and_b32_e32 v9, 0x7fffffff, v9
	v_and_b32_e32 v8, 0x7fffffff, v8
	v_and_b32_e32 v11, 0x7fffffff, v11
	v_and_b32_e32 v10, 0x7fffffff, v10
	v_and_b32_e32 v13, 0x7fffffff, v13
	v_and_b32_e32 v12, 0x7fffffff, v12
	v_and_b32_e32 v15, 0x7fffffff, v15
	v_and_b32_e32 v14, 0x7fffffff, v14
	v_mov_b32_e32 v139, v138
	s_mov_b32 s41, 0xc26c0000
	v_add_f32_e32 v81, -1.0, v0
	v_pk_mul_f32 v[94:95], v[14:15], v[138:139]
	v_pk_mul_f32 v[92:93], v[12:13], v[138:139]
	v_pk_mul_f32 v[90:91], v[10:11], v[138:139]
	v_pk_mul_f32 v[88:89], v[8:9], v[138:139]
	v_pk_mul_f32 v[86:87], v[6:7], v[138:139]
	v_pk_mul_f32 v[84:85], v[4:5], v[138:139]
	v_pk_mul_f32 v[82:83], v[2:3], v[138:139]
	v_pk_add_f32 v[2:3], v[0:1], s[40:41] op_sel_hi:[0,1]
	v_pk_add_f32 v[4:5], v[0:1], s[30:31] op_sel_hi:[0,1]
	v_pk_add_f32 v[6:7], v[0:1], s[26:27] op_sel_hi:[0,1]
	v_pk_add_f32 v[8:9], v[0:1], s[8:9] op_sel_hi:[0,1]
	v_pk_add_f32 v[10:11], v[0:1], s[10:11] op_sel_hi:[0,1]
	v_pk_add_f32 v[12:13], v[0:1], s[34:35] op_sel_hi:[0,1]
	v_pk_add_f32 v[14:15], v[0:1], s[14:15] op_sel_hi:[0,1]
	v_pk_add_f32 v[96:97], v[0:1], s[0:1] op_sel_hi:[0,1]
	v_and_b32_e32 v80, 0x7fffffff, v0
	v_and_b32_e32 v81, 0x7fffffff, v81
	v_and_b32_e32 v97, 0x7fffffff, v97
	v_and_b32_e32 v96, 0x7fffffff, v96
	v_and_b32_e32 v15, 0x7fffffff, v15
	v_and_b32_e32 v14, 0x7fffffff, v14
	v_and_b32_e32 v13, 0x7fffffff, v13
	v_and_b32_e32 v12, 0x7fffffff, v12
	v_and_b32_e32 v11, 0x7fffffff, v11
	v_and_b32_e32 v10, 0x7fffffff, v10
	v_and_b32_e32 v9, 0x7fffffff, v9
	v_and_b32_e32 v8, 0x7fffffff, v8
	v_and_b32_e32 v7, 0x7fffffff, v7
	v_and_b32_e32 v6, 0x7fffffff, v6
	v_and_b32_e32 v5, 0x7fffffff, v5
	v_and_b32_e32 v4, 0x7fffffff, v4
	v_and_b32_e32 v3, 0x7fffffff, v3
	v_and_b32_e32 v2, 0x7fffffff, v2
	v_pk_mul_f32 v[80:81], v[80:81], v[140:141]
	v_pk_mul_f32 v[110:111], v[2:3], v[138:139]
	v_pk_mul_f32 v[108:109], v[4:5], v[138:139]
	v_pk_mul_f32 v[106:107], v[6:7], v[138:139]
	v_pk_mul_f32 v[104:105], v[8:9], v[138:139]
	v_pk_mul_f32 v[102:103], v[10:11], v[138:139]
	v_pk_mul_f32 v[100:101], v[12:13], v[138:139]
	v_pk_mul_f32 v[98:99], v[14:15], v[138:139]
	v_pk_mul_f32 v[96:97], v[96:97], v[140:141]
	s_mov_b64 s[40:41], 0
